# layer-0 pre-norm (f32 input) row loop software-pipelined like the FFN pre-norms
# speedup vs baseline: 1.0059x; 1.0059x over previous
; __device__ __forceinline__ float bf_lo(unsigned w) { return __uint_as_float(w << 16); }
; __device__ __forceinline__ float bf_hi(unsigned w) { return __uint_as_float(w & 0xffff0000u); }
; template <int MODE, bool INBF> ...
;     ...
;         for (int i0 = 0; i0 < 8; i0 += RB) {
;             f32x4 v[RB][8];
; #pragma unroll
;             for (int q = 0; q < RB; ++q) { const int row = blk * 64 + wave + 8 * (i0 + q);
;                 if (INBF) { const u32x2* xr = (const u32x2*)((const bf16*)xin_ + (size_t)row * DM) + lane;
; #pragma unroll
;                     for (int j = 0; j < 8; ++j) { const u32x2 w = xr[64 * j]; v[q][j] = (f32x4){bf_lo(w.x), bf_hi(w.x), bf_lo(w.y), bf_hi(w.y)}; }
;                 } else { const f32x4* xr = (const f32x4*)((const float*)xin_ + (size_t)row * DM) + lane;
; #pragma unroll
;                     for (int j = 0; j < 8; ++j) v[q][j] = xr[64 * j]; } }
; #pragma unroll
;             for (int q = 0; q < RB; ++q) { const int row = blk * 64 + wave + 8 * (i0 + q); float ss = 0.f;
; #pragma unroll
;                 for (int j = 0; j < 8; ++j) ss += (v[q][j].x * v[q][j].x + v[q][j].y * v[q][j].y) + (v[q][j].z * v[q][j].z + v[q][j].w * v[q][j].w);
;                 const float rstd = 1.0f / sqrtf(wave_sum(ss) * (1.0f / DM) + EPS);
.LBB0_120:
	s_or_b64 exec, exec, s[6:7]
	s_ashr_i32 s11, s10, 31
	s_lshl_b64 s[6:7], s[10:11], 12
	v_lshl_add_u64 v[64:65], v[60:61], 0, s[6:7]
	s_lshl_b64 s[6:7], s[10:11], 13
	v_lshl_add_u64 v[66:67], v[62:63], 0, s[6:7]
	s_mov_b64 s[16:17], 0
	s_waitcnt lgkmcnt(0)
	s_barrier
	global_load_dwordx4 v[200:203], v[66:67], off
	global_load_dwordx4 v[204:207], v[66:67], off offset:1024
	global_load_dwordx4 v[208:211], v[66:67], off offset:2048
	global_load_dwordx4 v[212:215], v[66:67], off offset:3072
	global_load_dwordx4 v[216:219], v[66:67], off offset:-4096
	global_load_dwordx4 v[220:223], v[66:67], off offset:-3072
	global_load_dwordx4 v[224:227], v[66:67], off offset:-2048
	global_load_dwordx4 v[228:231], v[66:67], off offset:-1024
	s_waitcnt vmcnt(0)
.LBB0_121:
	v_add_co_u32_e32 v68, vcc, 0xfffff000, v66
	v_lshl_add_u64 v[106:107], v[64:65], 0, s[16:17]
	s_nop 0
	v_addc_co_u32_e32 v69, vcc, -1, v67, vcc
	v_add_co_u32_e32 v110, vcc, 0xfffff400, v66
	s_nop 0
	s_nop 0
	s_nop 0
	s_nop 0
	v_add_co_u32_e64 v122, s[6:7], s21, v106
	v_addc_co_u32_e32 v111, vcc, -1, v67, vcc
	ds_read_b128 v[16:19], v76
	ds_read_b128 v[20:23], v76 offset:1024
	ds_read_b128 v[24:27], v76 offset:8192
	ds_read_b128 v[28:31], v76 offset:9216
	ds_read_b128 v[32:35], v76 offset:2048
	ds_read_b128 v[36:39], v76 offset:3072
	ds_read_b128 v[40:43], v76 offset:10240
	ds_read_b128 v[44:47], v76 offset:11264
	ds_read_b128 v[48:51], v76 offset:4096
	ds_read_b128 v[52:55], v76 offset:5120
	ds_read_b128 v[82:85], v76 offset:12288
	ds_read_b128 v[86:89], v76 offset:13312
	ds_read_b128 v[90:93], v76 offset:6144
	ds_read_b128 v[94:97], v76 offset:7168
	ds_read_b128 v[98:101], v76 offset:14336
	ds_read_b128 v[102:105], v76 offset:15360
	v_addc_co_u32_e64 v123, s[6:7], 0, v107, s[6:7]
	s_nop 0
	s_add_u32 s16, s16, 0x8000
	s_nop 0
	v_add_co_u32_e32 v68, vcc, 0xfffff800, v66
	s_addc_u32 s17, s17, 0
	s_nop 0
	v_addc_co_u32_e32 v69, vcc, -1, v67, vcc
	v_add_co_u32_e32 v118, vcc, 0xfffffc00, v66
	s_nop 0
	s_nop 0
	v_addc_co_u32_e32 v119, vcc, -1, v67, vcc
	s_nop 0
	s_cmp_lg_u32 s16, 0x40000
	v_lshl_add_u64 v[66:67], v[66:67], 0, s[14:15]
	s_waitcnt vmcnt(8) lgkmcnt(0)
	v_mov_b32_e32 v12, v200
	v_mov_b32_e32 v13, v201
	v_mov_b32_e32 v14, v202
	v_mov_b32_e32 v15, v203
	v_mov_b32_e32 v8, v204
	v_mov_b32_e32 v9, v205
	v_mov_b32_e32 v10, v206
	v_mov_b32_e32 v11, v207
	v_mov_b32_e32 v4, v208
	v_mov_b32_e32 v5, v209
	v_mov_b32_e32 v6, v210
	v_mov_b32_e32 v7, v211
	v_mov_b32_e32 v0, v212
	v_mov_b32_e32 v1, v213
	v_mov_b32_e32 v2, v214
	v_mov_b32_e32 v3, v215
	v_mov_b32_e32 v106, v216
	v_mov_b32_e32 v107, v217
	v_mov_b32_e32 v108, v218
	v_mov_b32_e32 v109, v219
	v_mov_b32_e32 v110, v220
	v_mov_b32_e32 v111, v221
	v_mov_b32_e32 v112, v222
	v_mov_b32_e32 v113, v223
	v_mov_b32_e32 v114, v224
	v_mov_b32_e32 v115, v225
	v_mov_b32_e32 v116, v226
	v_mov_b32_e32 v117, v227
	v_mov_b32_e32 v118, v228
	v_mov_b32_e32 v119, v229
	v_mov_b32_e32 v120, v230
	v_mov_b32_e32 v121, v231
	s_cbranch_scc0 .Lnp_skip_n0
	global_load_dwordx4 v[200:203], v[66:67], off
	global_load_dwordx4 v[204:207], v[66:67], off offset:1024
	global_load_dwordx4 v[208:211], v[66:67], off offset:2048
	global_load_dwordx4 v[212:215], v[66:67], off offset:3072
	global_load_dwordx4 v[216:219], v[66:67], off offset:-4096
	global_load_dwordx4 v[220:223], v[66:67], off offset:-3072
	global_load_dwordx4 v[224:227], v[66:67], off offset:-2048
	global_load_dwordx4 v[228:231], v[66:67], off offset:-1024
.Lnp_skip_n0:
	v_mul_f32_e32 v138, v14, v14
	v_pk_mul_f32 v[68:69], v[10:11], v[10:11]
	v_pk_mul_f32 v[124:125], v[8:9], v[8:9]
	v_mul_f32_e32 v129, v2, v2
	v_mul_f32_e32 v126, v5, v5
	v_mul_f32_e32 v128, v7, v7
	v_mul_f32_e32 v133, v3, v3
	v_pk_mov_b32 v[130:131], v[124:125], v[68:69] op_sel:[1,0]
	v_mov_b32_e32 v125, v69
	v_pk_fma_f32 v[68:69], v[4:5], v[4:5], v[126:127] op_sel_hi:[1,1,0]
	v_pk_fma_f32 v[126:127], v[6:7], v[6:7], v[128:129] op_sel_hi:[1,1,0]
	v_mov_b32_e32 v132, v107
	v_mov_b32_e32 v69, v129
	v_mov_b32_e32 v127, v133
	v_mov_b32_e32 v134, v109
	v_mov_b32_e32 v133, v111
	v_mov_b32_e32 v135, v113
	v_mov_b32_e32 v128, v106
	v_pk_add_f32 v[124:125], v[130:131], v[124:125]
	v_mov_b32_e32 v130, v108
	v_mov_b32_e32 v129, v110
	v_mov_b32_e32 v131, v112
	v_pk_add_f32 v[68:69], v[68:69], v[126:127]
	v_pk_mul_f32 v[126:127], v[132:133], v[132:133]
	v_pk_mul_f32 v[132:133], v[134:135], v[134:135]
	v_pk_mul_f32 v[134:135], v[116:117], v[116:117]
	v_pk_mul_f32 v[136:137], v[114:115], v[114:115]
	v_pk_fma_f32 v[126:127], v[128:129], v[128:129], v[126:127]
	v_pk_fma_f32 v[128:129], v[130:131], v[130:131], v[132:133]
	v_pk_mov_b32 v[130:131], v[136:137], v[134:135] op_sel:[1,0]
	v_mov_b32_e32 v137, v135
	v_mul_f32_e32 v132, v119, v119
	v_mul_f32_e32 v134, v121, v121
	v_pk_add_f32 v[126:127], v[126:127], v[128:129]
	v_pk_add_f32 v[128:129], v[130:131], v[136:137]
	v_mul_f32_e32 v139, v15, v15
	v_mul_f32_e32 v140, v12, v12
	v_mul_f32_e32 v141, v13, v13
	v_pk_fma_f32 v[130:131], v[118:119], v[118:119], v[132:133] op_sel_hi:[1,1,0]
	v_pk_fma_f32 v[132:133], v[120:121], v[120:121], v[134:135] op_sel_hi:[1,1,0]
	v_pk_add_f32 v[126:127], v[126:127], v[126:127] op_sel:[0,1] op_sel_hi:[1,0]
	v_pk_add_f32 v[128:129], v[128:129], v[128:129] op_sel:[0,1] op_sel_hi:[1,0]
	v_mov_b32_e32 v131, v138
	v_mov_b32_e32 v133, v139
	v_mov_b32_e32 v127, v140
	v_mov_b32_e32 v129, v141
	v_pk_add_f32 v[130:131], v[130:131], v[132:133]
	v_pk_add_f32 v[126:127], v[126:127], v[128:129]
	v_mul_f32_e32 v142, v1, v1
	v_pk_add_f32 v[126:127], v[126:127], v[130:131]
	v_mul_f32_e32 v143, v0, v0
	v_pk_add_f32 v[124:125], v[124:125], v[124:125] op_sel:[0,1] op_sel_hi:[1,0]
	v_pk_add_f32 v[126:127], v[126:127], v[126:127] op_sel:[0,1] op_sel_hi:[1,0]
	v_mov_b32_e32 v125, v142
	v_mov_b32_e32 v127, v143
	v_pk_add_f32 v[124:125], v[126:127], v[124:125]
	s_nop 0
	v_pk_add_f32 v[68:69], v[124:125], v[68:69]
	s_nop 0
	v_add_f32_e32 v68, v68, v69
	s_nop 0
	s_waitcnt lgkmcnt(0)
; #define LAS __attribute__((address_space(3)))
; __device__ __forceinline__ unsigned pk_bf16(float lo, float hi) { unsigned r; asm volatile("v_cvt_pk_bf16_f32 %0, %1, %2" : "=v"(r) : "v"(lo), "v"(hi)); return r; }
; template <int MODE, bool INBF> ...
;     ...
;                 const float rstd = 1.0f / sqrtf(wave_sum(ss) * (1.0f / DM) + EPS);
; #pragma unroll
;                 for (int j = 0; j < 8; ++j) { const f32x4 a = *(const LAS f32x4*)(cA + 4 * (64 * j + lane)), bb = *(const LAS f32x4*)(cB + 4 * (64 * j + lane)); v[q][j] = (v[q][j] * rstd) * a + bb; }
;                 if (MODE == 1) { f32x4* o = (f32x4*)(outf + (size_t)row * DM) + lane;
; #pragma unroll
;                     for (int j = 0; j < 8; ++j) o[64 * j] = v[q][j];
;                 } else { u32x2* o = (u32x2*)(outb + (size_t)row * DM) + lane;
; #pragma unroll
;                     for (int j = 0; j < 8; ++j) { u32x2 w; w.x = pk_bf16(v[q][j].x, v[q][j].y); w.y = pk_bf16(v[q][j].z, v[q][j].w); o[64 * j] = w; } } }
	s_nop 1
	v_add_f32_dpp v68, v68, v68 quad_perm:[1,0,3,2] row_mask:0xf bank_mask:0xf
	s_nop 0
	s_waitcnt lgkmcnt(0)
	s_nop 1
	v_add_f32_dpp v68, v68, v68 quad_perm:[2,3,0,1] row_mask:0xf bank_mask:0xf
	s_nop 0
	s_waitcnt lgkmcnt(0)
	s_nop 1
	v_add_f32_dpp v68, v68, v68 row_half_mirror row_mask:0xf bank_mask:0xf
	s_nop 0
	s_waitcnt lgkmcnt(0)
	s_nop 1
	v_add_f32_dpp v68, v68, v68 row_mirror row_mask:0xf bank_mask:0xf
	v_mov_b32_e32 v69, v68
	s_waitcnt lgkmcnt(0)
	s_nop 1
	v_permlane16_swap_b32_e32 v68, v69
	v_add_f32_e32 v68, v68, v69
	v_mov_b32_e32 v69, v68
	s_waitcnt lgkmcnt(0)
	s_nop 1
	v_permlane32_swap_b32_e32 v68, v69
	v_add_f32_e32 v68, v68, v69
	v_fmamk_f32 v68, v68, 0x3a000000, v79
	v_mul_f32_e32 v69, 0x4f800000, v68
	v_cmp_gt_f32_e32 vcc, s20, v68
	s_nop 1
	v_cndmask_b32_e32 v68, v68, v69, vcc
	v_sqrt_f32_e32 v69, v68
	s_nop 0
	v_add_u32_e32 v124, -1, v69
	v_add_u32_e32 v125, 1, v69
	v_fma_f32 v126, -v124, v69, v68
	v_fma_f32 v127, -v125, v69, v68
	v_cmp_ge_f32_e64 s[6:7], 0, v126
	s_nop 1
	v_cndmask_b32_e64 v69, v69, v124, s[6:7]
	v_cmp_lt_f32_e64 s[6:7], 0, v127
	s_nop 1
	v_cndmask_b32_e64 v69, v69, v125, s[6:7]
	v_mul_f32_e32 v124, 0x37800000, v69
	v_cndmask_b32_e32 v69, v69, v124, vcc
	v_cmp_class_f32_e32 vcc, v68, v80
	s_nop 1
	v_cndmask_b32_e32 v68, v69, v68, vcc
	v_div_scale_f32 v69, s[6:7], v68, v68, 1.0
	v_rcp_f32_e32 v125, v69
	v_div_scale_f32 v124, vcc, 1.0, v68, 1.0
	v_fma_f32 v126, -v69, v125, 1.0
	v_fmac_f32_e32 v125, v126, v125
	v_mul_f32_e32 v126, v124, v125
	v_fma_f32 v127, -v69, v126, v124
	v_fmac_f32_e32 v126, v127, v125
	v_fma_f32 v69, -v69, v126, v124
	v_div_fmas_f32 v69, v69, v125, v126
	v_div_fixup_f32 v68, v69, v68, 1.0
	v_pk_mul_f32 v[106:107], v[106:107], v[68:69] op_sel_hi:[1,0]
	v_pk_mul_f32 v[108:109], v[108:109], v[68:69] op_sel_hi:[1,0]
	v_pk_fma_f32 v[16:17], v[16:17], v[106:107], v[24:25]
	v_pk_mul_f32 v[110:111], v[110:111], v[68:69] op_sel_hi:[1,0]
	v_pk_mul_f32 v[112:113], v[112:113], v[68:69] op_sel_hi:[1,0]
	v_pk_fma_f32 v[18:19], v[18:19], v[108:109], v[26:27]
	v_cvt_pk_bf16_f32 v16, v16, v17
	v_pk_mul_f32 v[114:115], v[114:115], v[68:69] op_sel_hi:[1,0]
	v_cvt_pk_bf16_f32 v17, v18, v19
	v_pk_mul_f32 v[116:117], v[116:117], v[68:69] op_sel_hi:[1,0]
	v_pk_mul_f32 v[12:13], v[12:13], v[68:69] op_sel_hi:[1,0]
	v_pk_mul_f32 v[8:9], v[8:9], v[68:69] op_sel_hi:[1,0]
	v_pk_mul_f32 v[4:5], v[4:5], v[68:69] op_sel_hi:[1,0]
	v_pk_mul_f32 v[0:1], v[0:1], v[68:69] op_sel_hi:[1,0]
	v_pk_fma_f32 v[22:23], v[22:23], v[112:113], v[30:31]
	v_pk_fma_f32 v[20:21], v[20:21], v[110:111], v[28:29]
	global_store_dwordx2 v[122:123], v[16:17], off
	v_cvt_pk_bf16_f32 v16, v20, v21
	v_cvt_pk_bf16_f32 v17, v22, v23
	v_pk_mul_f32 v[118:119], v[118:119], v[68:69] op_sel_hi:[1,0]
	v_pk_mul_f32 v[120:121], v[120:121], v[68:69] op_sel_hi:[1,0]
	v_pk_mul_f32 v[14:15], v[14:15], v[68:69] op_sel_hi:[1,0]
	v_pk_mul_f32 v[10:11], v[10:11], v[68:69] op_sel_hi:[1,0]
	v_pk_mul_f32 v[6:7], v[6:7], v[68:69] op_sel_hi:[1,0]
	v_pk_mul_f32 v[2:3], v[2:3], v[68:69] op_sel_hi:[1,0]
	v_pk_fma_f32 v[24:25], v[34:35], v[116:117], v[42:43]
	v_pk_fma_f32 v[26:27], v[32:33], v[114:115], v[40:41]
	v_pk_fma_f32 v[12:13], v[48:49], v[12:13], v[82:83]
	v_pk_fma_f32 v[8:9], v[52:53], v[8:9], v[86:87]
	v_pk_fma_f32 v[4:5], v[4:5], v[90:91], v[98:99]
	v_pk_fma_f32 v[0:1], v[0:1], v[94:95], v[102:103]
	global_store_dwordx2 v[122:123], v[16:17], off offset:512
	v_cvt_pk_bf16_f32 v16, v26, v27
	v_cvt_pk_bf16_f32 v17, v24, v25
	v_pk_fma_f32 v[28:29], v[38:39], v[120:121], v[46:47]
	v_pk_fma_f32 v[30:31], v[36:37], v[118:119], v[44:45]
	v_pk_fma_f32 v[14:15], v[50:51], v[14:15], v[84:85]
	v_pk_fma_f32 v[10:11], v[54:55], v[10:11], v[88:89]
	v_pk_fma_f32 v[6:7], v[6:7], v[92:93], v[100:101]
	v_pk_fma_f32 v[2:3], v[2:3], v[96:97], v[104:105]
	global_store_dwordx2 v[122:123], v[16:17], off offset:1024
	v_cvt_pk_bf16_f32 v16, v30, v31
	v_cvt_pk_bf16_f32 v17, v28, v29
	global_store_dwordx2 v[122:123], v[16:17], off offset:1536
	v_cvt_pk_bf16_f32 v12, v12, v13
	v_cvt_pk_bf16_f32 v13, v14, v15
	global_store_dwordx2 v[122:123], v[12:13], off offset:2048
	v_cvt_pk_bf16_f32 v8, v8, v9
	v_cvt_pk_bf16_f32 v9, v10, v11
	global_store_dwordx2 v[122:123], v[8:9], off offset:2560
	v_cvt_pk_bf16_f32 v4, v4, v5
	v_cvt_pk_bf16_f32 v5, v6, v7
	global_store_dwordx2 v[122:123], v[4:5], off offset:3072
	v_cvt_pk_bf16_f32 v0, v0, v1
	v_cvt_pk_bf16_f32 v1, v2, v3
	global_store_dwordx2 v[122:123], v[0:1], off offset:3584
	s_cbranch_scc1 .LBB0_121
	s_add_i32 s22, s22, s3
	s_add_i32 s10, s10, s18
	s_cmpk_lt_i32 s22, 0x100
	s_cbranch_scc1 .LBB0_117
